# baseline (speedup 1.0000x reference)
; #define LAS __attribute__((address_space(3)))
; DI unsigned pk_bf16(float lo, float hi) { unsigned r; asm("v_cvt_pk_bf16_f32 %0, %1, %2" : "=v"(r) : "v"(lo), "v"(hi)); return r; }
; #define MFMA32(a, b, c) __builtin_amdgcn_mfma_f32_32x32x16_bf16((a), (b), (c), 0, 0, 0)
; DI bf16x8 cat4(s16x4 lo, s16x4 hi) { return __builtin_shufflevector(lo, hi, 0, 1, 2, 3, 4, 5, 6, 7); }
; DI void attn_unit(const Params& P, LAS unsigned char* lds, int b, int h, int qb, bool dry) {
;     ...
;         f32x2_ ls2 = {0.f, 0.f};
;         const f32x2_ m2 = {mrun, mrun};
; #pragma unroll
;         for (int i = 0; i < 16; i += 2) {
;             f32x2_ t = (f32x2_){s0[i], s0[i + 1]} - m2; t.x = __builtin_amdgcn_exp2f(t.x); t.y = __builtin_amdgcn_exp2f(t.y); ls2 += t; s0[i] = t.x; s0[i + 1] = t.y;
;             f32x2_ u = (f32x2_){s1[i], s1[i + 1]} - m2; u.x = __builtin_amdgcn_exp2f(u.x); u.y = __builtin_amdgcn_exp2f(u.y); ls2 += u; s1[i] = u.x; s1[i + 1] = u.y;
;         }
;         lrun += ls2.x + ls2.y;
; #pragma unroll
;         for (int s2 = 0; s2 < 2; ++s2) {
;             u32x4 t0, t1;
;             t0.x = pk_bf16(s0[8 * s2 + 0], s0[8 * s2 + 1]); t0.y = pk_bf16(s0[8 * s2 + 2], s0[8 * s2 + 3]); t0.z = pk_bf16(s0[8 * s2 + 4], s0[8 * s2 + 5]); t0.w = pk_bf16(s0[8 * s2 + 6], s0[8 * s2 + 7]);
;             t1.x = pk_bf16(s1[8 * s2 + 0], s1[8 * s2 + 1]); t1.y = pk_bf16(s1[8 * s2 + 2], s1[8 * s2 + 3]); t1.z = pk_bf16(s1[8 * s2 + 4], s1[8 * s2 + 5]); t1.w = pk_bf16(s1[8 * s2 + 6], s1[8 * s2 + 7]);
;             pf[0][s2] = __builtin_bit_cast(bf16x8, t0); pf[1][s2] = __builtin_bit_cast(bf16x8, t1);
;         }
;     };
;     auto pv = [&](int vslot) {
;         const LAS unsigned char* vb_ = Vs + vslot * VS_BYTES + r * VS_STRIDE + 8 * hh;
; #pragma unroll
;         for (int kb = 0; kb < 2; ++kb)
; #pragma unroll
;             for (int s2 = 0; s2 < 2; ++s2)
; #pragma unroll
;                 for (int d = 0; d < 4; ++d) {
;                     const LAS unsigned char* p = vb_ + d * 32 * VS_STRIDE + (32 * kb + 16 * s2) * 2;
;                     const bf16x8 a = cat4(*(const LAS s16x4*)p, *(const LAS s16x4*)(p + 16));
;                     o[d] = MFMA32(a, pf[kb][s2], o[d]);
;                 }
.LBB0_40:
	v_add_u32_e32 v221, 0xc800, v216
	ds_read2_b64 v[222:225], v221 offset1:2
	v_add_u32_e32 v240, 0xf800, v216
	v_exp_f32_e32 v230, v86
	v_exp_f32_e32 v231, v87
	v_exp_f32_e32 v232, v88
	v_exp_f32_e32 v233, v89
	ds_read2_b64 v[86:89], v240 offset0:96 offset1:98
	v_exp_f32_e32 v234, v90
	v_exp_f32_e32 v235, v91
	v_add_u32_e32 v238, 0xd800, v216
	v_exp_f32_e32 v236, v92
	v_exp_f32_e32 v237, v93
	ds_read2_b64 v[90:93], v221 offset0:4 offset1:6
	v_exp_f32_e32 v80, v80
	v_exp_f32_e32 v81, v81
	v_exp_f32_e32 v82, v82
	v_exp_f32_e32 v83, v83
	v_exp_f32_e32 v84, v84
	v_exp_f32_e32 v85, v85
	v_cvt_pk_bf16_f32 v226, v80, v81
	v_cvt_pk_bf16_f32 v227, v82, v83
	v_cvt_pk_bf16_f32 v228, v84, v85
	v_cvt_pk_bf16_f32 v229, v230, v231
	v_add_u32_e32 v239, 0xe800, v216
	s_waitcnt lgkmcnt(0)
	v_mfma_f32_32x32x16_bf16 v[48:63], v[222:225], v[226:229], v[48:63]
	ds_read2_b64 v[222:225], v238 offset0:32 offset1:34
	v_mfma_f32_32x32x16_bf16 v[0:15], v[86:89], v[226:229], v[0:15]
	v_cvt_pk_bf16_f32 v88, v236, v237
	v_exp_f32_e32 v94, v94
	v_exp_f32_e32 v95, v95
	v_cvt_pk_bf16_f32 v86, v232, v233
	v_cvt_pk_bf16_f32 v87, v234, v235
	v_cvt_pk_bf16_f32 v89, v94, v95
	s_waitcnt lgkmcnt(0)
	v_mfma_f32_32x32x16_bf16 v[32:47], v[222:225], v[226:229], v[32:47]
	ds_read2_b64 v[222:225], v239 offset0:64 offset1:66
	v_mfma_f32_32x32x16_bf16 v[48:63], v[90:93], v[86:89], v[48:63]
	ds_read2_b64 v[90:93], v238 offset0:36 offset1:38
	s_waitcnt lgkmcnt(0)
	v_mfma_f32_32x32x16_bf16 v[32:47], v[90:93], v[86:89], v[32:47]
	ds_read2_b64 v[90:93], v239 offset0:68 offset1:70
	v_mfma_f32_32x32x16_bf16 v[16:31], v[222:225], v[226:229], v[16:31]
	v_exp_f32_e32 v226, v64
	v_exp_f32_e32 v227, v65
	ds_read2_b64 v[222:225], v240 offset0:100 offset1:102
	s_waitcnt lgkmcnt(0)
	v_mfma_f32_32x32x16_bf16 v[16:31], v[90:93], v[86:89], v[16:31]
	v_exp_f32_e32 v90, v66
	v_exp_f32_e32 v91, v67
	v_exp_f32_e32 v92, v68
	v_exp_f32_e32 v93, v69
	ds_read2_b64 v[64:67], v221 offset0:8 offset1:10
	v_mfma_f32_32x32x16_bf16 v[0:15], v[222:225], v[86:89], v[0:15]
	v_exp_f32_e32 v222, v70
	v_exp_f32_e32 v223, v71
	v_cvt_pk_bf16_f32 v68, v226, v227
	v_cvt_pk_bf16_f32 v69, v90, v91
	v_cvt_pk_bf16_f32 v70, v92, v93
	v_cvt_pk_bf16_f32 v71, v222, v223
	ds_read2_b64 v[86:89], v240 offset0:104 offset1:106
	s_waitcnt lgkmcnt(0)
	v_mfma_f32_32x32x16_bf16 v[48:63], v[64:67], v[68:71], v[48:63]
	ds_read2_b64 v[64:67], v238 offset0:40 offset1:42
	v_exp_f32_e32 v224, v72
	v_exp_f32_e32 v225, v73
	v_add_f32_e64 v72, v226, v80
	v_add_f32_e64 v73, v227, v81
	s_waitcnt lgkmcnt(0)
	v_mfma_f32_32x32x16_bf16 v[32:47], v[64:67], v[68:71], v[32:47]
	ds_read2_b64 v[64:67], v239 offset0:72 offset1:74
	v_add_f32_e64 v72, v82, v72
	v_add_f32_e64 v73, v83, v73
	v_add_f32_e64 v72, v90, v72
	v_add_f32_e64 v73, v91, v73
	v_add_f32_e64 v80, v84, v72
	v_add_f32_e64 v81, v85, v73
	s_waitcnt lgkmcnt(0)
	v_mfma_f32_32x32x16_bf16 v[16:31], v[64:67], v[68:71], v[16:31]
	v_exp_f32_e32 v228, v74
	v_exp_f32_e32 v229, v75
	ds_read2_b64 v[72:75], v239 offset0:76 offset1:78
	s_nop 0
	v_exp_f32_e32 v76, v76
	v_exp_f32_e32 v77, v77
	ds_read2_b64 v[64:67], v221 offset0:12 offset1:14
	v_mfma_f32_32x32x16_bf16 v[0:15], v[86:89], v[68:71], v[0:15]
	v_cvt_pk_bf16_f32 v70, v76, v77
	v_exp_f32_e32 v78, v78
	v_exp_f32_e32 v79, v79
	v_cvt_pk_bf16_f32 v68, v224, v225
	v_cvt_pk_bf16_f32 v69, v228, v229
	v_cvt_pk_bf16_f32 v71, v78, v79
	s_waitcnt lgkmcnt(0)
	s_nop 0
	v_mfma_f32_32x32x16_bf16 v[48:63], v[64:67], v[68:71], v[48:63]
	ds_read2_b64 v[64:67], v238 offset0:44 offset1:46
	s_waitcnt lgkmcnt(0)
	v_mfma_f32_32x32x16_bf16 v[32:47], v[64:67], v[68:71], v[32:47]
	v_add_f32_e64 v64, v92, v80
	v_add_f32_e64 v65, v93, v81
	v_add_f32_e64 v64, v230, v64
	v_add_f32_e64 v65, v231, v65
	v_add_f32_e64 v64, v222, v64
	v_add_f32_e64 v65, v223, v65
	v_add_f32_e64 v64, v232, v64
	v_add_f32_e64 v65, v233, v65
	v_mfma_f32_32x32x16_bf16 v[16:31], v[72:75], v[68:71], v[16:31]
	v_add_f32_e64 v64, v224, v64
	v_add_f32_e64 v65, v225, v65
	v_add_f32_e64 v80, v234, v64
	v_add_f32_e64 v81, v235, v65
	ds_read2_b64 v[64:67], v240 offset0:108 offset1:110
	v_add_f32_e64 v72, v228, v80
	v_add_f32_e64 v73, v229, v81
	s_nop 0
	v_add_f32_e64 v72, v236, v72
	v_add_f32_e64 v73, v237, v73
	s_waitcnt lgkmcnt(0)
	v_mfma_f32_32x32x16_bf16 v[0:15], v[64:67], v[68:71], v[0:15]
	v_add_f32_e64 v72, v76, v72
	v_add_f32_e64 v73, v77, v73
	v_add_f32_e64 v72, v94, v72
	v_add_f32_e64 v73, v95, v73
	v_add_f32_e64 v72, v78, v72
	v_add_f32_e64 v73, v79, v73
	v_add_f32_e32 v72, v72, v73
	v_add_f32_e32 v215, v215, v72
	s_branch .Lattn_wdone0

; #define LAS __attribute__((address_space(3)))
; DI unsigned pk_bf16(float lo, float hi) { unsigned r; asm("v_cvt_pk_bf16_f32 %0, %1, %2" : "=v"(r) : "v"(lo), "v"(hi)); return r; }
; #define MFMA32(a, b, c) __builtin_amdgcn_mfma_f32_32x32x16_bf16((a), (b), (c), 0, 0, 0)
; DI bf16x8 cat4(s16x4 lo, s16x4 hi) { return __builtin_shufflevector(lo, hi, 0, 1, 2, 3, 4, 5, 6, 7); }
; DI void attn_unit(const Params& P, LAS unsigned char* lds, int b, int h, int qb, bool dry) {
;     ...
;         f32x2_ ls2 = {0.f, 0.f};
;         const f32x2_ m2 = {mrun, mrun};
; #pragma unroll
;         for (int i = 0; i < 16; i += 2) {
;             f32x2_ t = (f32x2_){s0[i], s0[i + 1]} - m2; t.x = __builtin_amdgcn_exp2f(t.x); t.y = __builtin_amdgcn_exp2f(t.y); ls2 += t; s0[i] = t.x; s0[i + 1] = t.y;
;             f32x2_ u = (f32x2_){s1[i], s1[i + 1]} - m2; u.x = __builtin_amdgcn_exp2f(u.x); u.y = __builtin_amdgcn_exp2f(u.y); ls2 += u; s1[i] = u.x; s1[i + 1] = u.y;
;         }
;         lrun += ls2.x + ls2.y;
; #pragma unroll
;         for (int s2 = 0; s2 < 2; ++s2) {
;             u32x4 t0, t1;
;             t0.x = pk_bf16(s0[8 * s2 + 0], s0[8 * s2 + 1]); t0.y = pk_bf16(s0[8 * s2 + 2], s0[8 * s2 + 3]); t0.z = pk_bf16(s0[8 * s2 + 4], s0[8 * s2 + 5]); t0.w = pk_bf16(s0[8 * s2 + 6], s0[8 * s2 + 7]);
;             t1.x = pk_bf16(s1[8 * s2 + 0], s1[8 * s2 + 1]); t1.y = pk_bf16(s1[8 * s2 + 2], s1[8 * s2 + 3]); t1.z = pk_bf16(s1[8 * s2 + 4], s1[8 * s2 + 5]); t1.w = pk_bf16(s1[8 * s2 + 6], s1[8 * s2 + 7]);
;             pf[0][s2] = __builtin_bit_cast(bf16x8, t0); pf[1][s2] = __builtin_bit_cast(bf16x8, t1);
;         }
;     };
;     auto pv = [&](int vslot) {
;         const LAS unsigned char* vb_ = Vs + vslot * VS_BYTES + r * VS_STRIDE + 8 * hh;
; #pragma unroll
;         for (int kb = 0; kb < 2; ++kb)
; #pragma unroll
;             for (int s2 = 0; s2 < 2; ++s2)
; #pragma unroll
;                 for (int d = 0; d < 4; ++d) {
;                     const LAS unsigned char* p = vb_ + d * 32 * VS_STRIDE + (32 * kb + 16 * s2) * 2;
;                     const bf16x8 a = cat4(*(const LAS s16x4*)p, *(const LAS s16x4*)(p + 16));
;                     o[d] = MFMA32(a, pf[kb][s2], o[d]);
;                 }
.LBB0_49:
	ds_read2_b64 v[220:223], v218 offset1:2
	v_add_u32_e32 v238, 0x3000, v218
	v_exp_f32_e32 v228, v86
	v_exp_f32_e32 v229, v87
	v_exp_f32_e32 v230, v88
	v_exp_f32_e32 v231, v89
	ds_read2_b64 v[86:89], v238 offset0:96 offset1:98
	v_exp_f32_e32 v232, v90
	v_exp_f32_e32 v233, v91
	v_add_u32_e32 v236, 0x1000, v218
	v_exp_f32_e32 v234, v92
	v_exp_f32_e32 v235, v93
	ds_read2_b64 v[90:93], v218 offset0:4 offset1:6
	v_exp_f32_e32 v80, v80
	v_exp_f32_e32 v81, v81
	v_exp_f32_e32 v82, v82
	v_exp_f32_e32 v83, v83
	v_exp_f32_e32 v84, v84
	v_exp_f32_e32 v85, v85
	v_cvt_pk_bf16_f32 v224, v80, v81
	v_cvt_pk_bf16_f32 v225, v82, v83
	v_cvt_pk_bf16_f32 v226, v84, v85
	v_cvt_pk_bf16_f32 v227, v228, v229
	v_add_u32_e32 v237, 0x2000, v218
	s_waitcnt lgkmcnt(0)
	v_mfma_f32_32x32x16_bf16 v[48:63], v[220:223], v[224:227], v[48:63]
	ds_read2_b64 v[220:223], v236 offset0:32 offset1:34
	v_mfma_f32_32x32x16_bf16 v[0:15], v[86:89], v[224:227], v[0:15]
	v_cvt_pk_bf16_f32 v88, v234, v235
	v_exp_f32_e32 v94, v94
	v_exp_f32_e32 v95, v95
	v_cvt_pk_bf16_f32 v86, v230, v231
	v_cvt_pk_bf16_f32 v87, v232, v233
	v_cvt_pk_bf16_f32 v89, v94, v95
	s_waitcnt lgkmcnt(0)
	v_mfma_f32_32x32x16_bf16 v[32:47], v[220:223], v[224:227], v[32:47]
	ds_read2_b64 v[220:223], v237 offset0:64 offset1:66
	v_mfma_f32_32x32x16_bf16 v[48:63], v[90:93], v[86:89], v[48:63]
	ds_read2_b64 v[90:93], v236 offset0:36 offset1:38
	s_waitcnt lgkmcnt(0)
	v_mfma_f32_32x32x16_bf16 v[32:47], v[90:93], v[86:89], v[32:47]
	ds_read2_b64 v[90:93], v237 offset0:68 offset1:70
	v_mfma_f32_32x32x16_bf16 v[16:31], v[220:223], v[224:227], v[16:31]
	v_exp_f32_e32 v224, v64
	v_exp_f32_e32 v225, v65
	ds_read2_b64 v[220:223], v238 offset0:100 offset1:102
	s_waitcnt lgkmcnt(0)
	v_mfma_f32_32x32x16_bf16 v[16:31], v[90:93], v[86:89], v[16:31]
	v_exp_f32_e32 v90, v66
	v_exp_f32_e32 v91, v67
	v_exp_f32_e32 v92, v68
	v_exp_f32_e32 v93, v69
	ds_read2_b64 v[64:67], v218 offset0:8 offset1:10
	v_mfma_f32_32x32x16_bf16 v[0:15], v[220:223], v[86:89], v[0:15]
	v_exp_f32_e32 v220, v70
	v_exp_f32_e32 v221, v71
	v_cvt_pk_bf16_f32 v68, v224, v225
	v_cvt_pk_bf16_f32 v69, v90, v91
	v_cvt_pk_bf16_f32 v70, v92, v93
	v_cvt_pk_bf16_f32 v71, v220, v221
	ds_read2_b64 v[86:89], v238 offset0:104 offset1:106
	s_waitcnt lgkmcnt(0)
	v_mfma_f32_32x32x16_bf16 v[48:63], v[64:67], v[68:71], v[48:63]
	ds_read2_b64 v[64:67], v236 offset0:40 offset1:42
	v_exp_f32_e32 v222, v72
	v_exp_f32_e32 v223, v73
	v_add_f32_e64 v72, v224, v80
	v_add_f32_e64 v73, v225, v81
	s_waitcnt lgkmcnt(0)
	v_mfma_f32_32x32x16_bf16 v[32:47], v[64:67], v[68:71], v[32:47]
	ds_read2_b64 v[64:67], v237 offset0:72 offset1:74
	v_add_f32_e64 v72, v82, v72
	v_add_f32_e64 v73, v83, v73
	v_add_f32_e64 v72, v90, v72
	v_add_f32_e64 v73, v91, v73
	v_add_f32_e64 v80, v84, v72
	v_add_f32_e64 v81, v85, v73
	s_waitcnt lgkmcnt(0)
	v_mfma_f32_32x32x16_bf16 v[16:31], v[64:67], v[68:71], v[16:31]
	v_exp_f32_e32 v226, v74
	v_exp_f32_e32 v227, v75
	ds_read2_b64 v[72:75], v237 offset0:76 offset1:78
	s_nop 0
	v_exp_f32_e32 v76, v76
	v_exp_f32_e32 v77, v77
	ds_read2_b64 v[64:67], v218 offset0:12 offset1:14
	v_mfma_f32_32x32x16_bf16 v[0:15], v[86:89], v[68:71], v[0:15]
	v_cvt_pk_bf16_f32 v70, v76, v77
	v_exp_f32_e32 v78, v78
	v_exp_f32_e32 v79, v79
	v_cvt_pk_bf16_f32 v68, v222, v223
	v_cvt_pk_bf16_f32 v69, v226, v227
	v_cvt_pk_bf16_f32 v71, v78, v79
	s_waitcnt lgkmcnt(0)
	s_nop 0
	v_mfma_f32_32x32x16_bf16 v[48:63], v[64:67], v[68:71], v[48:63]
	ds_read2_b64 v[64:67], v236 offset0:44 offset1:46
	s_waitcnt lgkmcnt(0)
	v_mfma_f32_32x32x16_bf16 v[32:47], v[64:67], v[68:71], v[32:47]
	v_add_f32_e64 v64, v92, v80
	v_add_f32_e64 v65, v93, v81
	v_add_f32_e64 v64, v228, v64
	v_add_f32_e64 v65, v229, v65
	v_add_f32_e64 v64, v220, v64
	v_add_f32_e64 v65, v221, v65
	v_add_f32_e64 v64, v230, v64
	v_add_f32_e64 v65, v231, v65
	v_mfma_f32_32x32x16_bf16 v[16:31], v[72:75], v[68:71], v[16:31]
	v_add_f32_e64 v64, v222, v64
	v_add_f32_e64 v65, v223, v65
	v_add_f32_e64 v80, v232, v64
	v_add_f32_e64 v81, v233, v65
	ds_read2_b64 v[64:67], v238 offset0:108 offset1:110
	v_add_f32_e64 v72, v226, v80
	v_add_f32_e64 v73, v227, v81
	s_nop 0
	v_add_f32_e64 v72, v234, v72
	v_add_f32_e64 v73, v235, v73
	s_waitcnt lgkmcnt(0)
	v_mfma_f32_32x32x16_bf16 v[0:15], v[64:67], v[68:71], v[0:15]
	v_add_f32_e64 v72, v76, v72
	v_add_f32_e64 v73, v77, v73
	v_add_f32_e64 v72, v94, v72
	v_add_f32_e64 v73, v95, v73
	v_add_f32_e64 v72, v78, v72
	v_add_f32_e64 v73, v79, v73
	v_add_f32_e32 v72, v72, v73
	v_add_f32_e32 v215, v215, v72
	s_branch .LBB0_32
